# attention setup: do not wait for q_lat loads before issuing the first gathers
# baseline (speedup 1.0000x reference)
; __device__ __forceinline__ void attn_item(const Ptrs& P, unsigned char* lds, int b, int tq0, int tid) {
;     ...
;     const int q = w >> 1, half = w & 1, tq = tq0 + q;
;     const int nsel = tq + 1 < 256 ? tq + 1 : 256;
;     bf16x8 Af[8];
;     {
;         const bf16_t* qlp = P.QL + (rowb + tq) * 4096 + r16 * 256 + 8 * g;
; #pragma unroll
;         for (int ks = 0; ks < 8; ++ks) Af[ks] = *(const bf16x8*)(qlp + 32 * ks);
;     }
;     bf16_t* stw = stg + w * 32 * SP;
;     bf16_t* Pw = (bf16_t*)(l2 + 2048) + w * 16 * 40;
;     volatile unsigned* xa = (volatile unsigned*)(lds + 147456);
;     const unsigned aseq = (xa[40 + w] + 1u) & 0xffffu; if (lane == 0) xa[40 + w] = aseq;
.LBB0_921:
	s_or_b64 exec, exec, s[14:15]
	v_add_u32_e32 v220, v32, v124
	v_add_u32_e32 v164, s81, v220
	v_lshlrev_b64 v[0:1], 13, v[164:165]
	v_lshl_add_u64 v[184:185], s[76:77], 0, v[0:1]
	v_mov_b32_e32 v181, v165
	v_lshl_add_u64 v[0:1], v[184:185], 0, v[180:181]
	v_lshlrev_b32_e32 v164, 1, v166
	v_lshl_add_u64 v[28:29], v[0:1], 0, v[164:165]
	global_load_dwordx4 v[0:3], v[28:29], off
	global_load_dwordx4 v[4:7], v[28:29], off offset:64
	global_load_dwordx4 v[8:11], v[28:29], off offset:128
	global_load_dwordx4 v[12:15], v[28:29], off offset:192
	global_load_dwordx4 v[16:19], v[28:29], off offset:256
	global_load_dwordx4 v[20:23], v[28:29], off offset:320
	global_load_dwordx4 v[24:27], v[28:29], off offset:384
	s_nop 0
	global_load_dwordx4 v[28:31], v[28:29], off offset:448
	s_lshl_b32 s12, s62, 2
	s_add_i32 s16, s12, 0
	s_add_i32 s20, s16, 0x240a0
	v_mov_b64_e32 v[34:35], s[20:21]
	ds_read_b32 v33, v34
	s_waitcnt lgkmcnt(0)
	v_add_u32_e32 v33, 1, v33
	v_and_b32_e32 v218, 0xffff, v33
	s_and_saveexec_b64 s[12:13], s[4:5]
	s_cbranch_execz .LBB0_923
	v_mov_b64_e32 v[34:35], s[20:21]
	ds_write_b32 v34, v218
	s_waitcnt lgkmcnt(0)
